# sa2 + SwiGLU epilogue arithmetic issued as packed VOP3P f32 (v_pk_mul/v_pk_add on accumulator pairs), P2 and P9
# speedup vs baseline: 1.0102x; 1.0102x over previous
.LBB0_250:
	s_mov_b32 s100, 0xbfb8aa3b
	s_waitcnt vmcnt(0)
	s_lshl_b32 s17, s30, 4
	v_pk_mul_f32 v[156:157], v[124:125], s[100:101] op_sel_hi:[1,0]
	v_pk_mul_f32 v[158:159], v[126:127], s[100:101] op_sel_hi:[1,0]
	v_exp_f32_e32 v156, v156
	v_exp_f32_e32 v157, v157
	v_exp_f32_e32 v158, v158
	v_exp_f32_e32 v159, v159
	v_pk_add_f32 v[156:157], v[156:157], 1.0 op_sel_hi:[1,0]
	v_pk_add_f32 v[158:159], v[158:159], 1.0 op_sel_hi:[1,0]
	v_rcp_f32_e32 v156, v156
	v_rcp_f32_e32 v157, v157
	v_rcp_f32_e32 v158, v158
	v_rcp_f32_e32 v159, v159
	v_pk_mul_f32 v[156:157], v[124:125], v[156:157]
	v_pk_mul_f32 v[158:159], v[126:127], v[158:159]
	v_pk_mul_f32 v[156:157], v[156:157], v[116:117]
	v_pk_mul_f32 v[158:159], v[158:159], v[118:119]
	v_cvt_pk_bf16_f32 v116, v156, v157
	v_cvt_pk_bf16_f32 v117, v158, v159
	v_pk_mul_f32 v[156:157], v[120:121], s[100:101] op_sel_hi:[1,0]
	v_pk_mul_f32 v[158:159], v[122:123], s[100:101] op_sel_hi:[1,0]
	v_exp_f32_e32 v156, v156
	v_exp_f32_e32 v157, v157
	v_exp_f32_e32 v158, v158
	v_exp_f32_e32 v159, v159
	v_pk_add_f32 v[156:157], v[156:157], 1.0 op_sel_hi:[1,0]
	v_pk_add_f32 v[158:159], v[158:159], 1.0 op_sel_hi:[1,0]
	v_rcp_f32_e32 v156, v156
	v_rcp_f32_e32 v157, v157
	v_rcp_f32_e32 v158, v158
	v_rcp_f32_e32 v159, v159
	v_pk_mul_f32 v[156:157], v[120:121], v[156:157]
	v_pk_mul_f32 v[158:159], v[122:123], v[158:159]
	v_pk_mul_f32 v[156:157], v[156:157], v[112:113]
	v_pk_mul_f32 v[158:159], v[158:159], v[114:115]
	v_cvt_pk_bf16_f32 v120, v156, v157
	v_cvt_pk_bf16_f32 v115, v158, v159
	ds_bpermute_b32 v112, v151, v116
	ds_bpermute_b32 v113, v151, v117
	s_add_i32 s17, s17, s73
	s_lshl_b32 s30, s84, 2
	s_mul_hi_i32 s19, s17, 0x58
	s_mulk_i32 s17, 0x58
	s_ashr_i32 s33, s30, 31
	s_add_u32 s34, s17, s30
	ds_bpermute_b32 v114, v151, v120
	ds_bpermute_b32 v115, v151, v115
	s_addc_u32 s35, s19, s33
	s_or_b64 s[34:35], s[34:35], s[0:1]
	s_lshl_b64 s[34:35], s[34:35], 10
	v_lshl_add_u64 v[146:147], v[136:137], 0, s[34:35]
	v_pk_mul_f32 v[156:157], v[108:109], s[100:101] op_sel_hi:[1,0]
	v_pk_mul_f32 v[158:159], v[110:111], s[100:101] op_sel_hi:[1,0]
	v_exp_f32_e32 v156, v156
	v_exp_f32_e32 v157, v157
	v_exp_f32_e32 v158, v158
	v_exp_f32_e32 v159, v159
	v_pk_add_f32 v[156:157], v[156:157], 1.0 op_sel_hi:[1,0]
	v_pk_add_f32 v[158:159], v[158:159], 1.0 op_sel_hi:[1,0]
	v_rcp_f32_e32 v156, v156
	v_rcp_f32_e32 v157, v157
	v_rcp_f32_e32 v158, v158
	v_rcp_f32_e32 v159, v159
	v_pk_mul_f32 v[156:157], v[108:109], v[156:157]
	v_pk_mul_f32 v[158:159], v[110:111], v[158:159]
	v_pk_mul_f32 v[156:157], v[156:157], v[100:101]
	v_pk_mul_f32 v[158:159], v[158:159], v[102:103]
	s_waitcnt lgkmcnt(0)
	global_store_dwordx4 v[146:147], v[112:115], off
	v_cvt_pk_bf16_f32 v100, v156, v157
	s_mov_b32 s17, 0x16000
	v_cvt_pk_bf16_f32 v101, v158, v159
	v_pk_mul_f32 v[156:157], v[104:105], s[100:101] op_sel_hi:[1,0]
	v_pk_mul_f32 v[158:159], v[106:107], s[100:101] op_sel_hi:[1,0]
	v_exp_f32_e32 v156, v156
	v_exp_f32_e32 v157, v157
	v_exp_f32_e32 v158, v158
	v_exp_f32_e32 v159, v159
	v_pk_add_f32 v[156:157], v[156:157], 1.0 op_sel_hi:[1,0]
	v_pk_add_f32 v[158:159], v[158:159], 1.0 op_sel_hi:[1,0]
	v_rcp_f32_e32 v156, v156
	v_rcp_f32_e32 v157, v157
	v_rcp_f32_e32 v158, v158
	v_rcp_f32_e32 v159, v159
	v_pk_mul_f32 v[156:157], v[104:105], v[156:157]
	v_pk_mul_f32 v[158:159], v[106:107], v[158:159]
	v_pk_mul_f32 v[156:157], v[156:157], v[96:97]
	v_pk_mul_f32 v[158:159], v[158:159], v[98:99]
	v_cvt_pk_bf16_f32 v104, v156, v157
	v_cvt_pk_bf16_f32 v99, v158, v159
	ds_bpermute_b32 v96, v151, v100
	ds_bpermute_b32 v97, v151, v101
	ds_bpermute_b32 v98, v151, v104
	ds_bpermute_b32 v99, v151, v99
	v_add_co_u32_e32 v100, vcc, s17, v146
	s_nop 0
	v_addc_co_u32_e32 v101, vcc, 0, v147, vcc
	v_pk_mul_f32 v[156:157], v[92:93], s[100:101] op_sel_hi:[1,0]
	v_pk_mul_f32 v[158:159], v[94:95], s[100:101] op_sel_hi:[1,0]
	v_exp_f32_e32 v156, v156
	v_exp_f32_e32 v157, v157
	v_exp_f32_e32 v158, v158
	v_exp_f32_e32 v159, v159
	v_pk_add_f32 v[156:157], v[156:157], 1.0 op_sel_hi:[1,0]
	v_pk_add_f32 v[158:159], v[158:159], 1.0 op_sel_hi:[1,0]
	v_rcp_f32_e32 v156, v156
	v_rcp_f32_e32 v157, v157
	v_rcp_f32_e32 v158, v158
	v_rcp_f32_e32 v159, v159
	v_pk_mul_f32 v[156:157], v[92:93], v[156:157]
	v_pk_mul_f32 v[158:159], v[94:95], v[158:159]
	v_pk_mul_f32 v[156:157], v[156:157], v[84:85]
	v_pk_mul_f32 v[158:159], v[158:159], v[86:87]
	s_waitcnt lgkmcnt(0)
	global_store_dwordx4 v[100:101], v[96:99], off
	v_cvt_pk_bf16_f32 v84, v156, v157
	v_cvt_pk_bf16_f32 v85, v158, v159
	v_pk_mul_f32 v[156:157], v[88:89], s[100:101] op_sel_hi:[1,0]
	v_pk_mul_f32 v[158:159], v[90:91], s[100:101] op_sel_hi:[1,0]
	v_exp_f32_e32 v156, v156
	v_exp_f32_e32 v157, v157
	v_exp_f32_e32 v158, v158
	v_exp_f32_e32 v159, v159
	v_pk_add_f32 v[156:157], v[156:157], 1.0 op_sel_hi:[1,0]
	v_pk_add_f32 v[158:159], v[158:159], 1.0 op_sel_hi:[1,0]
	v_rcp_f32_e32 v156, v156
	v_rcp_f32_e32 v157, v157
	v_rcp_f32_e32 v158, v158
	v_rcp_f32_e32 v159, v159
	v_pk_mul_f32 v[156:157], v[88:89], v[156:157]
	v_pk_mul_f32 v[158:159], v[90:91], v[158:159]
	v_pk_mul_f32 v[156:157], v[156:157], v[80:81]
	v_pk_mul_f32 v[158:159], v[158:159], v[82:83]
	v_cvt_pk_bf16_f32 v88, v156, v157
	v_cvt_pk_bf16_f32 v83, v158, v159
	ds_bpermute_b32 v80, v151, v84
	ds_bpermute_b32 v81, v151, v85
	ds_bpermute_b32 v82, v151, v88
	ds_bpermute_b32 v83, v151, v83
	v_add_co_u32_e32 v84, vcc, s78, v146
	s_nop 0
	v_addc_co_u32_e32 v85, vcc, 0, v147, vcc
	v_pk_mul_f32 v[156:157], v[76:77], s[100:101] op_sel_hi:[1,0]
	v_pk_mul_f32 v[158:159], v[78:79], s[100:101] op_sel_hi:[1,0]
	v_exp_f32_e32 v156, v156
	v_exp_f32_e32 v157, v157
	v_exp_f32_e32 v158, v158
	v_exp_f32_e32 v159, v159
	v_pk_add_f32 v[156:157], v[156:157], 1.0 op_sel_hi:[1,0]
	v_pk_add_f32 v[158:159], v[158:159], 1.0 op_sel_hi:[1,0]
	v_rcp_f32_e32 v156, v156
	v_rcp_f32_e32 v157, v157
	v_rcp_f32_e32 v158, v158
	v_rcp_f32_e32 v159, v159
	v_pk_mul_f32 v[156:157], v[76:77], v[156:157]
	v_pk_mul_f32 v[158:159], v[78:79], v[158:159]
	v_pk_mul_f32 v[156:157], v[156:157], v[68:69]
	v_pk_mul_f32 v[158:159], v[158:159], v[70:71]
	s_waitcnt lgkmcnt(0)
	global_store_dwordx4 v[84:85], v[80:83], off
	v_cvt_pk_bf16_f32 v68, v156, v157
	v_cvt_pk_bf16_f32 v69, v158, v159
	v_pk_mul_f32 v[156:157], v[72:73], s[100:101] op_sel_hi:[1,0]
	v_pk_mul_f32 v[158:159], v[74:75], s[100:101] op_sel_hi:[1,0]
	v_exp_f32_e32 v156, v156
	v_exp_f32_e32 v157, v157
	v_exp_f32_e32 v158, v158
	v_exp_f32_e32 v159, v159
	v_pk_add_f32 v[156:157], v[156:157], 1.0 op_sel_hi:[1,0]
	v_pk_add_f32 v[158:159], v[158:159], 1.0 op_sel_hi:[1,0]
	v_rcp_f32_e32 v156, v156
	v_rcp_f32_e32 v157, v157
	v_rcp_f32_e32 v158, v158
	v_rcp_f32_e32 v159, v159
	v_pk_mul_f32 v[156:157], v[72:73], v[156:157]
	v_pk_mul_f32 v[158:159], v[74:75], v[158:159]
	v_pk_mul_f32 v[156:157], v[156:157], v[64:65]
	v_pk_mul_f32 v[158:159], v[158:159], v[66:67]
	v_cvt_pk_bf16_f32 v72, v156, v157
	v_cvt_pk_bf16_f32 v67, v158, v159
	ds_bpermute_b32 v64, v151, v68
	ds_bpermute_b32 v65, v151, v69
	ds_bpermute_b32 v66, v151, v72
	ds_bpermute_b32 v67, v151, v67
	v_add_co_u32_e32 v68, vcc, s79, v146
	s_nop 0
	v_addc_co_u32_e32 v69, vcc, 0, v147, vcc
	v_pk_mul_f32 v[156:157], v[60:61], s[100:101] op_sel_hi:[1,0]
	v_pk_mul_f32 v[158:159], v[62:63], s[100:101] op_sel_hi:[1,0]
	v_exp_f32_e32 v156, v156
	v_exp_f32_e32 v157, v157
	v_exp_f32_e32 v158, v158
	v_exp_f32_e32 v159, v159
	v_pk_add_f32 v[156:157], v[156:157], 1.0 op_sel_hi:[1,0]
	v_pk_add_f32 v[158:159], v[158:159], 1.0 op_sel_hi:[1,0]
	v_rcp_f32_e32 v156, v156
	v_rcp_f32_e32 v157, v157
	v_rcp_f32_e32 v158, v158
	v_rcp_f32_e32 v159, v159
	v_pk_mul_f32 v[156:157], v[60:61], v[156:157]
	v_pk_mul_f32 v[158:159], v[62:63], v[158:159]
	v_pk_mul_f32 v[156:157], v[156:157], v[52:53]
	v_pk_mul_f32 v[158:159], v[158:159], v[54:55]
	s_waitcnt lgkmcnt(0)
	global_store_dwordx4 v[68:69], v[64:67], off
	v_cvt_pk_bf16_f32 v52, v156, v157
	v_cvt_pk_bf16_f32 v53, v158, v159
	v_pk_mul_f32 v[156:157], v[56:57], s[100:101] op_sel_hi:[1,0]
	v_pk_mul_f32 v[158:159], v[58:59], s[100:101] op_sel_hi:[1,0]
	v_exp_f32_e32 v156, v156
	v_exp_f32_e32 v157, v157
	v_exp_f32_e32 v158, v158
	v_exp_f32_e32 v159, v159
	v_pk_add_f32 v[156:157], v[156:157], 1.0 op_sel_hi:[1,0]
	v_pk_add_f32 v[158:159], v[158:159], 1.0 op_sel_hi:[1,0]
	v_rcp_f32_e32 v156, v156
	v_rcp_f32_e32 v157, v157
	v_rcp_f32_e32 v158, v158
	v_rcp_f32_e32 v159, v159
	v_pk_mul_f32 v[156:157], v[56:57], v[156:157]
	v_pk_mul_f32 v[158:159], v[58:59], v[158:159]
	v_pk_mul_f32 v[156:157], v[156:157], v[48:49]
	v_pk_mul_f32 v[158:159], v[158:159], v[50:51]
	v_cvt_pk_bf16_f32 v56, v156, v157
	v_cvt_pk_bf16_f32 v51, v158, v159
	ds_bpermute_b32 v48, v151, v52
	ds_bpermute_b32 v49, v151, v53
	ds_bpermute_b32 v50, v151, v56
	ds_bpermute_b32 v51, v151, v51
	v_add_co_u32_e32 v52, vcc, s80, v146
	s_nop 0
	v_addc_co_u32_e32 v53, vcc, 0, v147, vcc
	v_pk_mul_f32 v[156:157], v[44:45], s[100:101] op_sel_hi:[1,0]
	v_pk_mul_f32 v[158:159], v[46:47], s[100:101] op_sel_hi:[1,0]
	v_exp_f32_e32 v156, v156
	v_exp_f32_e32 v157, v157
	v_exp_f32_e32 v158, v158
	v_exp_f32_e32 v159, v159
	v_pk_add_f32 v[156:157], v[156:157], 1.0 op_sel_hi:[1,0]
	v_pk_add_f32 v[158:159], v[158:159], 1.0 op_sel_hi:[1,0]
	v_rcp_f32_e32 v156, v156
	v_rcp_f32_e32 v157, v157
	v_rcp_f32_e32 v158, v158
	v_rcp_f32_e32 v159, v159
	v_pk_mul_f32 v[156:157], v[44:45], v[156:157]
	v_pk_mul_f32 v[158:159], v[46:47], v[158:159]
	v_pk_mul_f32 v[156:157], v[156:157], v[36:37]
	v_pk_mul_f32 v[158:159], v[158:159], v[38:39]
	s_waitcnt lgkmcnt(0)
	global_store_dwordx4 v[52:53], v[48:51], off
	v_cvt_pk_bf16_f32 v36, v156, v157
	v_cvt_pk_bf16_f32 v37, v158, v159
	v_pk_mul_f32 v[156:157], v[40:41], s[100:101] op_sel_hi:[1,0]
	v_pk_mul_f32 v[158:159], v[42:43], s[100:101] op_sel_hi:[1,0]
	v_exp_f32_e32 v156, v156
	v_exp_f32_e32 v157, v157
	v_exp_f32_e32 v158, v158
	v_exp_f32_e32 v159, v159
	v_pk_add_f32 v[156:157], v[156:157], 1.0 op_sel_hi:[1,0]
	v_pk_add_f32 v[158:159], v[158:159], 1.0 op_sel_hi:[1,0]
	v_rcp_f32_e32 v156, v156
	v_rcp_f32_e32 v157, v157
	v_rcp_f32_e32 v158, v158
	v_rcp_f32_e32 v159, v159
	v_pk_mul_f32 v[156:157], v[40:41], v[156:157]
	v_pk_mul_f32 v[158:159], v[42:43], v[158:159]
	v_pk_mul_f32 v[156:157], v[156:157], v[32:33]
	v_pk_mul_f32 v[158:159], v[158:159], v[34:35]
	v_cvt_pk_bf16_f32 v40, v156, v157
	v_cvt_pk_bf16_f32 v35, v158, v159
	ds_bpermute_b32 v32, v151, v36
	ds_bpermute_b32 v33, v151, v37
	ds_bpermute_b32 v34, v151, v40
	ds_bpermute_b32 v35, v151, v35
	v_add_co_u32_e32 v36, vcc, s81, v146
	s_nop 0
	v_addc_co_u32_e32 v37, vcc, 0, v147, vcc
	v_pk_mul_f32 v[156:157], v[28:29], s[100:101] op_sel_hi:[1,0]
	v_pk_mul_f32 v[158:159], v[30:31], s[100:101] op_sel_hi:[1,0]
	v_exp_f32_e32 v156, v156
	v_exp_f32_e32 v157, v157
	v_exp_f32_e32 v158, v158
	v_exp_f32_e32 v159, v159
	v_pk_add_f32 v[156:157], v[156:157], 1.0 op_sel_hi:[1,0]
	v_pk_add_f32 v[158:159], v[158:159], 1.0 op_sel_hi:[1,0]
	v_rcp_f32_e32 v156, v156
	v_rcp_f32_e32 v157, v157
	v_rcp_f32_e32 v158, v158
	v_rcp_f32_e32 v159, v159
	v_pk_mul_f32 v[156:157], v[28:29], v[156:157]
	v_pk_mul_f32 v[158:159], v[30:31], v[158:159]
	v_pk_mul_f32 v[156:157], v[156:157], v[20:21]
	v_pk_mul_f32 v[158:159], v[158:159], v[22:23]
	s_waitcnt lgkmcnt(0)
	global_store_dwordx4 v[36:37], v[32:35], off
	v_cvt_pk_bf16_f32 v20, v156, v157
	v_cvt_pk_bf16_f32 v21, v158, v159
	v_pk_mul_f32 v[156:157], v[24:25], s[100:101] op_sel_hi:[1,0]
	v_pk_mul_f32 v[158:159], v[26:27], s[100:101] op_sel_hi:[1,0]
	v_exp_f32_e32 v156, v156
	v_exp_f32_e32 v157, v157
	v_exp_f32_e32 v158, v158
	v_exp_f32_e32 v159, v159
	v_pk_add_f32 v[156:157], v[156:157], 1.0 op_sel_hi:[1,0]
	v_pk_add_f32 v[158:159], v[158:159], 1.0 op_sel_hi:[1,0]
	v_rcp_f32_e32 v156, v156
	v_rcp_f32_e32 v157, v157
	v_rcp_f32_e32 v158, v158
	v_rcp_f32_e32 v159, v159
	v_pk_mul_f32 v[156:157], v[24:25], v[156:157]
	v_pk_mul_f32 v[158:159], v[26:27], v[158:159]
	v_pk_mul_f32 v[156:157], v[156:157], v[16:17]
	v_pk_mul_f32 v[158:159], v[158:159], v[18:19]
	v_cvt_pk_bf16_f32 v24, v156, v157
	v_cvt_pk_bf16_f32 v19, v158, v159
	ds_bpermute_b32 v16, v151, v20
	ds_bpermute_b32 v17, v151, v21
	ds_bpermute_b32 v18, v151, v24
	ds_bpermute_b32 v19, v151, v19
	v_add_co_u32_e32 v20, vcc, s82, v146
	s_nop 0
	v_addc_co_u32_e32 v21, vcc, 0, v147, vcc
	v_pk_mul_f32 v[156:157], v[12:13], s[100:101] op_sel_hi:[1,0]
	v_pk_mul_f32 v[158:159], v[14:15], s[100:101] op_sel_hi:[1,0]
	v_exp_f32_e32 v156, v156
	v_exp_f32_e32 v157, v157
	v_exp_f32_e32 v158, v158
	v_exp_f32_e32 v159, v159
	v_pk_add_f32 v[156:157], v[156:157], 1.0 op_sel_hi:[1,0]
	v_pk_add_f32 v[158:159], v[158:159], 1.0 op_sel_hi:[1,0]
	v_rcp_f32_e32 v156, v156
	v_rcp_f32_e32 v157, v157
	v_rcp_f32_e32 v158, v158
	v_rcp_f32_e32 v159, v159
	v_pk_mul_f32 v[156:157], v[12:13], v[156:157]
	v_pk_mul_f32 v[158:159], v[14:15], v[158:159]
	v_pk_mul_f32 v[156:157], v[156:157], v[4:5]
	v_pk_mul_f32 v[158:159], v[158:159], v[6:7]
	s_waitcnt lgkmcnt(0)
	global_store_dwordx4 v[20:21], v[16:19], off
	v_cvt_pk_bf16_f32 v4, v156, v157
	v_cvt_pk_bf16_f32 v5, v158, v159
	v_pk_mul_f32 v[156:157], v[8:9], s[100:101] op_sel_hi:[1,0]
	v_pk_mul_f32 v[158:159], v[10:11], s[100:101] op_sel_hi:[1,0]
	v_exp_f32_e32 v156, v156
	v_exp_f32_e32 v157, v157
	v_exp_f32_e32 v158, v158
	v_exp_f32_e32 v159, v159
	v_pk_add_f32 v[156:157], v[156:157], 1.0 op_sel_hi:[1,0]
	v_pk_add_f32 v[158:159], v[158:159], 1.0 op_sel_hi:[1,0]
	v_rcp_f32_e32 v156, v156
	v_rcp_f32_e32 v157, v157
	v_rcp_f32_e32 v158, v158
	v_rcp_f32_e32 v159, v159
	v_pk_mul_f32 v[156:157], v[8:9], v[156:157]
	v_pk_mul_f32 v[158:159], v[10:11], v[158:159]
	v_pk_mul_f32 v[156:157], v[156:157], v[0:1]
	v_pk_mul_f32 v[158:159], v[158:159], v[2:3]
	v_cvt_pk_bf16_f32 v8, v156, v157
	v_cvt_pk_bf16_f32 v3, v158, v159
	ds_bpermute_b32 v0, v151, v4
	ds_bpermute_b32 v1, v151, v5
	ds_bpermute_b32 v2, v151, v8
	ds_bpermute_b32 v3, v151, v3
	v_add_co_u32_e32 v4, vcc, 0xf2000, v146
	s_nop 1
	v_addc_co_u32_e32 v5, vcc, 0, v147, vcc
	s_andn2_b64 vcc, exec, s[4:5]
	s_mov_b64 s[4:5], -1
	s_waitcnt lgkmcnt(0)
	global_store_dwordx4 v[4:5], v[0:3], off
	s_cbranch_vccnz .LBB0_243
	s_andn2_b64 vcc, exec, s[6:7]
	s_cbranch_vccnz .LBB0_242
	s_barrier
	s_branch .LBB0_242

.LBB0_1050:
	s_mov_b32 s100, 0xbfb8aa3b
	s_waitcnt vmcnt(0)
	s_lshl_b32 s17, s24, 4
	v_pk_mul_f32 v[156:157], v[124:125], s[100:101] op_sel_hi:[1,0]
	v_pk_mul_f32 v[158:159], v[126:127], s[100:101] op_sel_hi:[1,0]
	v_exp_f32_e32 v156, v156
	v_exp_f32_e32 v157, v157
	v_exp_f32_e32 v158, v158
	v_exp_f32_e32 v159, v159
	v_pk_add_f32 v[156:157], v[156:157], 1.0 op_sel_hi:[1,0]
	v_pk_add_f32 v[158:159], v[158:159], 1.0 op_sel_hi:[1,0]
	v_rcp_f32_e32 v156, v156
	v_rcp_f32_e32 v157, v157
	v_rcp_f32_e32 v158, v158
	v_rcp_f32_e32 v159, v159
	v_pk_mul_f32 v[156:157], v[124:125], v[156:157]
	v_pk_mul_f32 v[158:159], v[126:127], v[158:159]
	v_pk_mul_f32 v[156:157], v[156:157], v[116:117]
	v_pk_mul_f32 v[158:159], v[158:159], v[118:119]
	v_cvt_pk_bf16_f32 v116, v156, v157
	v_cvt_pk_bf16_f32 v117, v158, v159
	v_pk_mul_f32 v[156:157], v[120:121], s[100:101] op_sel_hi:[1,0]
	v_pk_mul_f32 v[158:159], v[122:123], s[100:101] op_sel_hi:[1,0]
	v_exp_f32_e32 v156, v156
	v_exp_f32_e32 v157, v157
	v_exp_f32_e32 v158, v158
	v_exp_f32_e32 v159, v159
	v_pk_add_f32 v[156:157], v[156:157], 1.0 op_sel_hi:[1,0]
	v_pk_add_f32 v[158:159], v[158:159], 1.0 op_sel_hi:[1,0]
	v_rcp_f32_e32 v156, v156
	v_rcp_f32_e32 v157, v157
	v_rcp_f32_e32 v158, v158
	v_rcp_f32_e32 v159, v159
	v_pk_mul_f32 v[156:157], v[120:121], v[156:157]
	v_pk_mul_f32 v[158:159], v[122:123], v[158:159]
	v_pk_mul_f32 v[156:157], v[156:157], v[112:113]
	v_pk_mul_f32 v[158:159], v[158:159], v[114:115]
	v_cvt_pk_bf16_f32 v120, v156, v157
	v_cvt_pk_bf16_f32 v115, v158, v159
	ds_bpermute_b32 v112, v151, v116
	ds_bpermute_b32 v113, v151, v117
	s_add_i32 s17, s17, s52
	s_lshl_b32 s24, s69, 2
	s_mul_hi_i32 s19, s17, 0x58
	s_mulk_i32 s17, 0x58
	s_ashr_i32 s27, s24, 31
	s_add_u32 s26, s17, s24
	ds_bpermute_b32 v114, v151, v120
	ds_bpermute_b32 v115, v151, v115
	s_addc_u32 s27, s19, s27
	s_or_b64 s[26:27], s[26:27], s[0:1]
	s_lshl_b64 s[26:27], s[26:27], 10
	v_lshl_add_u64 v[146:147], v[136:137], 0, s[26:27]
	v_pk_mul_f32 v[156:157], v[108:109], s[100:101] op_sel_hi:[1,0]
	v_pk_mul_f32 v[158:159], v[110:111], s[100:101] op_sel_hi:[1,0]
	v_exp_f32_e32 v156, v156
	v_exp_f32_e32 v157, v157
	v_exp_f32_e32 v158, v158
	v_exp_f32_e32 v159, v159
	v_pk_add_f32 v[156:157], v[156:157], 1.0 op_sel_hi:[1,0]
	v_pk_add_f32 v[158:159], v[158:159], 1.0 op_sel_hi:[1,0]
	v_rcp_f32_e32 v156, v156
	v_rcp_f32_e32 v157, v157
	v_rcp_f32_e32 v158, v158
	v_rcp_f32_e32 v159, v159
	v_pk_mul_f32 v[156:157], v[108:109], v[156:157]
	v_pk_mul_f32 v[158:159], v[110:111], v[158:159]
	v_pk_mul_f32 v[156:157], v[156:157], v[100:101]
	v_pk_mul_f32 v[158:159], v[158:159], v[102:103]
	s_waitcnt lgkmcnt(0)
	global_store_dwordx4 v[146:147], v[112:115], off
	v_cvt_pk_bf16_f32 v100, v156, v157
	v_cvt_pk_bf16_f32 v101, v158, v159
	v_pk_mul_f32 v[156:157], v[104:105], s[100:101] op_sel_hi:[1,0]
	v_pk_mul_f32 v[158:159], v[106:107], s[100:101] op_sel_hi:[1,0]
	v_exp_f32_e32 v156, v156
	v_exp_f32_e32 v157, v157
	v_exp_f32_e32 v158, v158
	v_exp_f32_e32 v159, v159
	v_pk_add_f32 v[156:157], v[156:157], 1.0 op_sel_hi:[1,0]
	v_pk_add_f32 v[158:159], v[158:159], 1.0 op_sel_hi:[1,0]
	v_rcp_f32_e32 v156, v156
	v_rcp_f32_e32 v157, v157
	v_rcp_f32_e32 v158, v158
	v_rcp_f32_e32 v159, v159
	v_pk_mul_f32 v[156:157], v[104:105], v[156:157]
	v_pk_mul_f32 v[158:159], v[106:107], v[158:159]
	v_pk_mul_f32 v[156:157], v[156:157], v[96:97]
	v_pk_mul_f32 v[158:159], v[158:159], v[98:99]
	v_cvt_pk_bf16_f32 v104, v156, v157
	v_cvt_pk_bf16_f32 v99, v158, v159
	ds_bpermute_b32 v96, v151, v100
	ds_bpermute_b32 v97, v151, v101
	ds_bpermute_b32 v98, v151, v104
	ds_bpermute_b32 v99, v151, v99
	v_add_co_u32_e32 v100, vcc, s49, v146
	s_nop 0
	v_addc_co_u32_e32 v101, vcc, 0, v147, vcc
	v_pk_mul_f32 v[156:157], v[92:93], s[100:101] op_sel_hi:[1,0]
	v_pk_mul_f32 v[158:159], v[94:95], s[100:101] op_sel_hi:[1,0]
	v_exp_f32_e32 v156, v156
	v_exp_f32_e32 v157, v157
	v_exp_f32_e32 v158, v158
	v_exp_f32_e32 v159, v159
	v_pk_add_f32 v[156:157], v[156:157], 1.0 op_sel_hi:[1,0]
	v_pk_add_f32 v[158:159], v[158:159], 1.0 op_sel_hi:[1,0]
	v_rcp_f32_e32 v156, v156
	v_rcp_f32_e32 v157, v157
	v_rcp_f32_e32 v158, v158
	v_rcp_f32_e32 v159, v159
	v_pk_mul_f32 v[156:157], v[92:93], v[156:157]
	v_pk_mul_f32 v[158:159], v[94:95], v[158:159]
	v_pk_mul_f32 v[156:157], v[156:157], v[84:85]
	v_pk_mul_f32 v[158:159], v[158:159], v[86:87]
	s_waitcnt lgkmcnt(0)
	global_store_dwordx4 v[100:101], v[96:99], off
	v_cvt_pk_bf16_f32 v84, v156, v157
	v_cvt_pk_bf16_f32 v85, v158, v159
	v_pk_mul_f32 v[156:157], v[88:89], s[100:101] op_sel_hi:[1,0]
	v_pk_mul_f32 v[158:159], v[90:91], s[100:101] op_sel_hi:[1,0]
	v_exp_f32_e32 v156, v156
	v_exp_f32_e32 v157, v157
	v_exp_f32_e32 v158, v158
	v_exp_f32_e32 v159, v159
	v_pk_add_f32 v[156:157], v[156:157], 1.0 op_sel_hi:[1,0]
	v_pk_add_f32 v[158:159], v[158:159], 1.0 op_sel_hi:[1,0]
	v_rcp_f32_e32 v156, v156
	v_rcp_f32_e32 v157, v157
	v_rcp_f32_e32 v158, v158
	v_rcp_f32_e32 v159, v159
	v_pk_mul_f32 v[156:157], v[88:89], v[156:157]
	v_pk_mul_f32 v[158:159], v[90:91], v[158:159]
	v_pk_mul_f32 v[156:157], v[156:157], v[80:81]
	v_pk_mul_f32 v[158:159], v[158:159], v[82:83]
	v_cvt_pk_bf16_f32 v88, v156, v157
	v_cvt_pk_bf16_f32 v83, v158, v159
	ds_bpermute_b32 v80, v151, v84
	ds_bpermute_b32 v81, v151, v85
	ds_bpermute_b32 v82, v151, v88
	ds_bpermute_b32 v83, v151, v83
	v_add_co_u32_e32 v84, vcc, s57, v146
	s_nop 0
	v_addc_co_u32_e32 v85, vcc, 0, v147, vcc
	v_pk_mul_f32 v[156:157], v[76:77], s[100:101] op_sel_hi:[1,0]
	v_pk_mul_f32 v[158:159], v[78:79], s[100:101] op_sel_hi:[1,0]
	v_exp_f32_e32 v156, v156
	v_exp_f32_e32 v157, v157
	v_exp_f32_e32 v158, v158
	v_exp_f32_e32 v159, v159
	v_pk_add_f32 v[156:157], v[156:157], 1.0 op_sel_hi:[1,0]
	v_pk_add_f32 v[158:159], v[158:159], 1.0 op_sel_hi:[1,0]
	v_rcp_f32_e32 v156, v156
	v_rcp_f32_e32 v157, v157
	v_rcp_f32_e32 v158, v158
	v_rcp_f32_e32 v159, v159
	v_pk_mul_f32 v[156:157], v[76:77], v[156:157]
	v_pk_mul_f32 v[158:159], v[78:79], v[158:159]
	v_pk_mul_f32 v[156:157], v[156:157], v[68:69]
	v_pk_mul_f32 v[158:159], v[158:159], v[70:71]
	s_waitcnt lgkmcnt(0)
	global_store_dwordx4 v[84:85], v[80:83], off
	v_cvt_pk_bf16_f32 v68, v156, v157
	v_cvt_pk_bf16_f32 v69, v158, v159
	v_pk_mul_f32 v[156:157], v[72:73], s[100:101] op_sel_hi:[1,0]
	v_pk_mul_f32 v[158:159], v[74:75], s[100:101] op_sel_hi:[1,0]
	v_exp_f32_e32 v156, v156
	v_exp_f32_e32 v157, v157
	v_exp_f32_e32 v158, v158
	v_exp_f32_e32 v159, v159
	v_pk_add_f32 v[156:157], v[156:157], 1.0 op_sel_hi:[1,0]
	v_pk_add_f32 v[158:159], v[158:159], 1.0 op_sel_hi:[1,0]
	v_rcp_f32_e32 v156, v156
	v_rcp_f32_e32 v157, v157
	v_rcp_f32_e32 v158, v158
	v_rcp_f32_e32 v159, v159
	v_pk_mul_f32 v[156:157], v[72:73], v[156:157]
	v_pk_mul_f32 v[158:159], v[74:75], v[158:159]
	v_pk_mul_f32 v[156:157], v[156:157], v[64:65]
	v_pk_mul_f32 v[158:159], v[158:159], v[66:67]
	v_cvt_pk_bf16_f32 v72, v156, v157
	v_cvt_pk_bf16_f32 v67, v158, v159
	ds_bpermute_b32 v64, v151, v68
	ds_bpermute_b32 v65, v151, v69
	ds_bpermute_b32 v66, v151, v72
	ds_bpermute_b32 v67, v151, v67
	v_add_co_u32_e32 v68, vcc, s58, v146
	s_nop 0
	v_addc_co_u32_e32 v69, vcc, 0, v147, vcc
	v_pk_mul_f32 v[156:157], v[60:61], s[100:101] op_sel_hi:[1,0]
	v_pk_mul_f32 v[158:159], v[62:63], s[100:101] op_sel_hi:[1,0]
	v_exp_f32_e32 v156, v156
	v_exp_f32_e32 v157, v157
	v_exp_f32_e32 v158, v158
	v_exp_f32_e32 v159, v159
	v_pk_add_f32 v[156:157], v[156:157], 1.0 op_sel_hi:[1,0]
	v_pk_add_f32 v[158:159], v[158:159], 1.0 op_sel_hi:[1,0]
	v_rcp_f32_e32 v156, v156
	v_rcp_f32_e32 v157, v157
	v_rcp_f32_e32 v158, v158
	v_rcp_f32_e32 v159, v159
	v_pk_mul_f32 v[156:157], v[60:61], v[156:157]
	v_pk_mul_f32 v[158:159], v[62:63], v[158:159]
	v_pk_mul_f32 v[156:157], v[156:157], v[52:53]
	v_pk_mul_f32 v[158:159], v[158:159], v[54:55]
	s_waitcnt lgkmcnt(0)
	global_store_dwordx4 v[68:69], v[64:67], off
	v_cvt_pk_bf16_f32 v52, v156, v157
	v_cvt_pk_bf16_f32 v53, v158, v159
	v_pk_mul_f32 v[156:157], v[56:57], s[100:101] op_sel_hi:[1,0]
	v_pk_mul_f32 v[158:159], v[58:59], s[100:101] op_sel_hi:[1,0]
	v_exp_f32_e32 v156, v156
	v_exp_f32_e32 v157, v157
	v_exp_f32_e32 v158, v158
	v_exp_f32_e32 v159, v159
	v_pk_add_f32 v[156:157], v[156:157], 1.0 op_sel_hi:[1,0]
	v_pk_add_f32 v[158:159], v[158:159], 1.0 op_sel_hi:[1,0]
	v_rcp_f32_e32 v156, v156
	v_rcp_f32_e32 v157, v157
	v_rcp_f32_e32 v158, v158
	v_rcp_f32_e32 v159, v159
	v_pk_mul_f32 v[156:157], v[56:57], v[156:157]
	v_pk_mul_f32 v[158:159], v[58:59], v[158:159]
	v_pk_mul_f32 v[156:157], v[156:157], v[48:49]
	v_pk_mul_f32 v[158:159], v[158:159], v[50:51]
	v_cvt_pk_bf16_f32 v56, v156, v157
	v_cvt_pk_bf16_f32 v51, v158, v159
	ds_bpermute_b32 v48, v151, v52
	ds_bpermute_b32 v49, v151, v53
	ds_bpermute_b32 v50, v151, v56
	ds_bpermute_b32 v51, v151, v51
	v_add_co_u32_e32 v52, vcc, s59, v146
	s_nop 0
	v_addc_co_u32_e32 v53, vcc, 0, v147, vcc
	v_pk_mul_f32 v[156:157], v[44:45], s[100:101] op_sel_hi:[1,0]
	v_pk_mul_f32 v[158:159], v[46:47], s[100:101] op_sel_hi:[1,0]
	v_exp_f32_e32 v156, v156
	v_exp_f32_e32 v157, v157
	v_exp_f32_e32 v158, v158
	v_exp_f32_e32 v159, v159
	v_pk_add_f32 v[156:157], v[156:157], 1.0 op_sel_hi:[1,0]
	v_pk_add_f32 v[158:159], v[158:159], 1.0 op_sel_hi:[1,0]
	v_rcp_f32_e32 v156, v156
	v_rcp_f32_e32 v157, v157
	v_rcp_f32_e32 v158, v158
	v_rcp_f32_e32 v159, v159
	v_pk_mul_f32 v[156:157], v[44:45], v[156:157]
	v_pk_mul_f32 v[158:159], v[46:47], v[158:159]
	v_pk_mul_f32 v[156:157], v[156:157], v[36:37]
	v_pk_mul_f32 v[158:159], v[158:159], v[38:39]
	s_waitcnt lgkmcnt(0)
	global_store_dwordx4 v[52:53], v[48:51], off
	v_cvt_pk_bf16_f32 v36, v156, v157
	v_cvt_pk_bf16_f32 v37, v158, v159
	v_pk_mul_f32 v[156:157], v[40:41], s[100:101] op_sel_hi:[1,0]
	v_pk_mul_f32 v[158:159], v[42:43], s[100:101] op_sel_hi:[1,0]
	v_exp_f32_e32 v156, v156
	v_exp_f32_e32 v157, v157
	v_exp_f32_e32 v158, v158
	v_exp_f32_e32 v159, v159
	v_pk_add_f32 v[156:157], v[156:157], 1.0 op_sel_hi:[1,0]
	v_pk_add_f32 v[158:159], v[158:159], 1.0 op_sel_hi:[1,0]
	v_rcp_f32_e32 v156, v156
	v_rcp_f32_e32 v157, v157
	v_rcp_f32_e32 v158, v158
	v_rcp_f32_e32 v159, v159
	v_pk_mul_f32 v[156:157], v[40:41], v[156:157]
	v_pk_mul_f32 v[158:159], v[42:43], v[158:159]
	v_pk_mul_f32 v[156:157], v[156:157], v[32:33]
	v_pk_mul_f32 v[158:159], v[158:159], v[34:35]
	v_cvt_pk_bf16_f32 v40, v156, v157
	v_cvt_pk_bf16_f32 v35, v158, v159
	ds_bpermute_b32 v32, v151, v36
	ds_bpermute_b32 v33, v151, v37
	ds_bpermute_b32 v34, v151, v40
	ds_bpermute_b32 v35, v151, v35
	v_add_co_u32_e32 v36, vcc, s60, v146
	s_nop 0
	v_addc_co_u32_e32 v37, vcc, 0, v147, vcc
	v_pk_mul_f32 v[156:157], v[28:29], s[100:101] op_sel_hi:[1,0]
	v_pk_mul_f32 v[158:159], v[30:31], s[100:101] op_sel_hi:[1,0]
	v_exp_f32_e32 v156, v156
	v_exp_f32_e32 v157, v157
	v_exp_f32_e32 v158, v158
	v_exp_f32_e32 v159, v159
	v_pk_add_f32 v[156:157], v[156:157], 1.0 op_sel_hi:[1,0]
	v_pk_add_f32 v[158:159], v[158:159], 1.0 op_sel_hi:[1,0]
	v_rcp_f32_e32 v156, v156
	v_rcp_f32_e32 v157, v157
	v_rcp_f32_e32 v158, v158
	v_rcp_f32_e32 v159, v159
	v_pk_mul_f32 v[156:157], v[28:29], v[156:157]
	v_pk_mul_f32 v[158:159], v[30:31], v[158:159]
	v_pk_mul_f32 v[156:157], v[156:157], v[20:21]
	v_pk_mul_f32 v[158:159], v[158:159], v[22:23]
	s_waitcnt lgkmcnt(0)
	global_store_dwordx4 v[36:37], v[32:35], off
	v_cvt_pk_bf16_f32 v20, v156, v157
	v_cvt_pk_bf16_f32 v21, v158, v159
	v_pk_mul_f32 v[156:157], v[24:25], s[100:101] op_sel_hi:[1,0]
	v_pk_mul_f32 v[158:159], v[26:27], s[100:101] op_sel_hi:[1,0]
	v_exp_f32_e32 v156, v156
	v_exp_f32_e32 v157, v157
	v_exp_f32_e32 v158, v158
	v_exp_f32_e32 v159, v159
	v_pk_add_f32 v[156:157], v[156:157], 1.0 op_sel_hi:[1,0]
	v_pk_add_f32 v[158:159], v[158:159], 1.0 op_sel_hi:[1,0]
	v_rcp_f32_e32 v156, v156
	v_rcp_f32_e32 v157, v157
	v_rcp_f32_e32 v158, v158
	v_rcp_f32_e32 v159, v159
	v_pk_mul_f32 v[156:157], v[24:25], v[156:157]
	v_pk_mul_f32 v[158:159], v[26:27], v[158:159]
	v_pk_mul_f32 v[156:157], v[156:157], v[16:17]
	v_pk_mul_f32 v[158:159], v[158:159], v[18:19]
	v_cvt_pk_bf16_f32 v24, v156, v157
	v_cvt_pk_bf16_f32 v19, v158, v159
	ds_bpermute_b32 v16, v151, v20
	ds_bpermute_b32 v17, v151, v21
	ds_bpermute_b32 v18, v151, v24
	ds_bpermute_b32 v19, v151, v19
	v_add_co_u32_e32 v20, vcc, s61, v146
	s_nop 0
	v_addc_co_u32_e32 v21, vcc, 0, v147, vcc
	v_pk_mul_f32 v[156:157], v[12:13], s[100:101] op_sel_hi:[1,0]
	v_pk_mul_f32 v[158:159], v[14:15], s[100:101] op_sel_hi:[1,0]
	v_exp_f32_e32 v156, v156
	v_exp_f32_e32 v157, v157
	v_exp_f32_e32 v158, v158
	v_exp_f32_e32 v159, v159
	v_pk_add_f32 v[156:157], v[156:157], 1.0 op_sel_hi:[1,0]
	v_pk_add_f32 v[158:159], v[158:159], 1.0 op_sel_hi:[1,0]
	v_rcp_f32_e32 v156, v156
	v_rcp_f32_e32 v157, v157
	v_rcp_f32_e32 v158, v158
	v_rcp_f32_e32 v159, v159
	v_pk_mul_f32 v[156:157], v[12:13], v[156:157]
	v_pk_mul_f32 v[158:159], v[14:15], v[158:159]
	v_pk_mul_f32 v[156:157], v[156:157], v[4:5]
	v_pk_mul_f32 v[158:159], v[158:159], v[6:7]
	s_waitcnt lgkmcnt(0)
	global_store_dwordx4 v[20:21], v[16:19], off
	v_cvt_pk_bf16_f32 v4, v156, v157
	v_cvt_pk_bf16_f32 v5, v158, v159
	v_pk_mul_f32 v[156:157], v[8:9], s[100:101] op_sel_hi:[1,0]
	v_pk_mul_f32 v[158:159], v[10:11], s[100:101] op_sel_hi:[1,0]
	v_exp_f32_e32 v156, v156
	v_exp_f32_e32 v157, v157
	v_exp_f32_e32 v158, v158
	v_exp_f32_e32 v159, v159
	v_pk_add_f32 v[156:157], v[156:157], 1.0 op_sel_hi:[1,0]
	v_pk_add_f32 v[158:159], v[158:159], 1.0 op_sel_hi:[1,0]
	v_rcp_f32_e32 v156, v156
	v_rcp_f32_e32 v157, v157
	v_rcp_f32_e32 v158, v158
	v_rcp_f32_e32 v159, v159
	v_pk_mul_f32 v[156:157], v[8:9], v[156:157]
	v_pk_mul_f32 v[158:159], v[10:11], v[158:159]
	v_pk_mul_f32 v[156:157], v[156:157], v[0:1]
	v_pk_mul_f32 v[158:159], v[158:159], v[2:3]
	v_cvt_pk_bf16_f32 v8, v156, v157
	v_cvt_pk_bf16_f32 v3, v158, v159
	ds_bpermute_b32 v0, v151, v4
	ds_bpermute_b32 v1, v151, v5
	ds_bpermute_b32 v2, v151, v8
	ds_bpermute_b32 v3, v151, v3
	v_add_co_u32_e32 v4, vcc, 0xf2000, v146
	s_nop 1
	v_addc_co_u32_e32 v5, vcc, 0, v147, vcc
	s_andn2_b64 vcc, exec, s[4:5]
	s_mov_b64 s[4:5], -1
	s_waitcnt lgkmcnt(0)
	global_store_dwordx4 v[4:5], v[0:3], off
	s_cbranch_vccnz .LBB0_1043
	s_andn2_b64 vcc, exec, s[6:7]
	s_cbranch_vccnz .LBB0_1042
	s_barrier
	s_branch .LBB0_1042
